# rownorm row loop software-pipelined: next row's 16 loads prefetched into spare VGPRs (mid and layer-0 tail sites)
# baseline (speedup 1.0000x reference)
; DI float bflo(unsigned u) { return __uint_as_float(u << 16); }
; DI float bfhi(unsigned u) { return __uint_as_float(u & 0xffff0000u); }
; DI void rownorm_phase(const Params& P, const float* xin, const bf16_t* yin, float* xout, bf16_t* hout, int lg, int gate_idx, const float* w_post,
;                       int lh, int scale_idx, int shift_idx, const float* w_pre, char* smem) {
;     ...
;   for (int row = blockIdx.x * 8 + w; row < S_; row += gridDim.x * 8) {
;     f32x4 xv[8];
; #pragma unroll
;     for (int j = 0; j < 8; ++j) xv[j] = __builtin_nontemporal_load((const f32x4*)(xin + (size_t)row * 2048 + (j * 64 + lane) * 4));
;     if (yin) {
;       f32x4 yv[8]; float ss = 0.f;
; #pragma unroll
;       for (int j = 0; j < 8; ++j) { const u32x2 yb = __builtin_nontemporal_load((const u32x2*)(yin + (size_t)row * 2048 + (j * 64 + lane) * 4)); yv[j] = (f32x4){bflo(yb.x), bfhi(yb.x), bflo(yb.y), bfhi(yb.y)};
.LBB0_887:
	s_or_b64 exec, exec, s[0:1]
	v_ashrrev_i32_e32 v0, 6, v2
	v_readlane_b32 s0, v254, 3
	s_waitcnt lgkmcnt(0)
	s_barrier
	v_add_u32_e32 v36, s0, v0
	s_movk_i32 s0, 0x4000
	v_cmp_gt_i32_e32 vcc, s0, v36
	s_and_saveexec_b64 s[0:1], vcc
	s_movk_i32 s96, 0x5ff
	s_movk_i32 s10, 0x3fff
	s_cbranch_execz .LBB0_890
	v_and_b32_e32 v5, 64, v239
	v_xor_b32_e32 v3, 32, v239
	v_add_u32_e32 v5, 64, v5
	v_cmp_lt_i32_e32 vcc, v3, v5
	v_and_b32_e32 v0, 63, v2
	v_lshlrev_b32_e32 v2, 2, v0
	v_cndmask_b32_e32 v3, v239, v3, vcc
	v_lshlrev_b32_e32 v96, 2, v3
	v_xor_b32_e32 v3, 16, v239
	v_cmp_lt_i32_e32 vcc, v3, v5
	v_readlane_b32 s8, v254, 61
	v_lshlrev_b32_e32 v95, 4, v0
	v_cndmask_b32_e32 v3, v239, v3, vcc
	v_lshlrev_b32_e32 v97, 2, v3
	v_xor_b32_e32 v3, 8, v239
	v_cmp_lt_i32_e32 vcc, v3, v5
	v_or_b32_e32 v4, 0x400, v2
	v_or_b32_e32 v6, 0x500, v2
	v_cndmask_b32_e32 v3, v239, v3, vcc
	v_lshlrev_b32_e32 v98, 2, v3
	v_xor_b32_e32 v3, 4, v239
	v_cmp_lt_i32_e32 vcc, v3, v5
	v_or_b32_e32 v8, 0x600, v2
	v_or_b32_e32 v10, 0x700, v2
	v_cndmask_b32_e32 v3, v239, v3, vcc
	v_lshlrev_b32_e32 v99, 2, v3
	v_xor_b32_e32 v3, 2, v239
	v_cmp_lt_i32_e32 vcc, v3, v5
	v_lshlrev_b32_e32 v0, 3, v0
	v_readlane_b32 s9, v254, 62
	v_cndmask_b32_e32 v3, v239, v3, vcc
	v_lshlrev_b32_e32 v100, 2, v3
	v_xor_b32_e32 v3, 1, v239
	v_cmp_lt_i32_e32 vcc, v3, v5
	v_lshl_add_u64 v[38:39], s[8:9], 0, v[0:1]
	v_lshl_add_u64 v[40:41], s[60:61], 0, v[0:1]
	v_cndmask_b32_e32 v3, v239, v3, vcc
	v_lshlrev_b32_e32 v101, 2, v3
	s_mov_b64 s[8:9], 0
	v_lshlrev_b32_e32 v0, 2, v2
	v_lshlrev_b32_e32 v42, 2, v4
	v_lshlrev_b32_e32 v44, 2, v6
	v_lshlrev_b32_e32 v46, 2, v8
	v_lshlrev_b32_e32 v48, 2, v10
	s_waitcnt vmcnt(0)
	v_mov_b32_e32 v43, v1
	v_mov_b32_e32 v45, v1
	v_mov_b32_e32 v47, v1
	v_mov_b32_e32 v49, v1
	v_ashrrev_i32_e32 v141, 31, v36
	v_mov_b32_e32 v140, v36
	v_lshlrev_b64 v[142:143], 13, v[140:141]
	v_lshl_add_u64 v[142:143], v[34:35], 0, v[142:143]
	v_lshlrev_b64 v[144:145], 12, v[140:141]
	v_lshl_add_u64 v[146:147], v[142:143], 0, v[0:1]
	v_lshl_add_u64 v[144:145], v[38:39], 0, v[144:145]
	global_load_dwordx4 v[160:163], v[146:147], off nt
	global_load_dwordx4 v[164:167], v[146:147], off offset:1024 nt
	global_load_dwordx4 v[168:171], v[146:147], off offset:2048 nt
	global_load_dwordx4 v[172:175], v[146:147], off offset:3072 nt
	global_load_dwordx2 v[124:125], v[144:145], off nt
	v_lshl_add_u64 v[146:147], v[142:143], 0, v[42:43]
	global_load_dwordx4 v[176:179], v[146:147], off nt
	v_lshl_add_u64 v[146:147], v[142:143], 0, v[44:45]
	global_load_dwordx4 v[180:183], v[146:147], off nt
	v_lshl_add_u64 v[146:147], v[142:143], 0, v[46:47]
	global_load_dwordx4 v[184:187], v[146:147], off nt
	v_lshl_add_u64 v[146:147], v[142:143], 0, v[48:49]
	global_load_dwordx4 v[188:191], v[146:147], off nt
	global_load_dwordx2 v[126:127], v[144:145], off offset:512 nt
	global_load_dwordx2 v[128:129], v[144:145], off offset:1024 nt
	global_load_dwordx2 v[130:131], v[144:145], off offset:1536 nt
	global_load_dwordx2 v[132:133], v[144:145], off offset:2048 nt
	global_load_dwordx2 v[134:135], v[144:145], off offset:2560 nt
	global_load_dwordx2 v[136:137], v[144:145], off offset:3072 nt
	global_load_dwordx2 v[138:139], v[144:145], off offset:3584 nt
.LBB0_889:
	v_ashrrev_i32_e32 v37, 31, v36
	v_lshlrev_b64 v[2:3], 13, v[36:37]
	v_lshl_add_u64 v[2:3], v[34:35], 0, v[2:3]
	v_lshlrev_b64 v[50:51], 12, v[36:37]
	v_lshl_add_u64 v[52:53], v[2:3], 0, v[0:1]
	v_mov_b32_e32 v43, v1
	v_mov_b32_e32 v45, v1
	v_mov_b32_e32 v47, v1
	v_mov_b32_e32 v49, v1
	v_lshl_add_u64 v[54:55], v[2:3], 0, v[42:43]
	v_lshl_add_u64 v[56:57], v[2:3], 0, v[44:45]
	v_lshl_add_u64 v[58:59], v[2:3], 0, v[46:47]
	v_lshl_add_u64 v[60:61], v[2:3], 0, v[48:49]
	s_waitcnt vmcnt(0)
	v_mov_b64_e32 v[30:31], v[160:161]
	v_mov_b64_e32 v[32:33], v[162:163]
	v_mov_b64_e32 v[26:27], v[164:165]
	v_mov_b64_e32 v[28:29], v[166:167]
	v_mov_b64_e32 v[22:23], v[168:169]
	v_mov_b64_e32 v[24:25], v[170:171]
	v_mov_b64_e32 v[18:19], v[172:173]
	v_mov_b64_e32 v[20:21], v[174:175]
	v_mov_b64_e32 v[14:15], v[176:177]
	v_mov_b64_e32 v[16:17], v[178:179]
	v_mov_b64_e32 v[10:11], v[180:181]
	v_mov_b64_e32 v[12:13], v[182:183]
	v_mov_b64_e32 v[6:7], v[184:185]
	v_mov_b64_e32 v[8:9], v[186:187]
	v_mov_b64_e32 v[2:3], v[188:189]
	v_mov_b64_e32 v[4:5], v[190:191]
	v_mov_b64_e32 v[62:63], v[124:125]
	v_mov_b64_e32 v[106:107], v[126:127]
	v_mov_b64_e32 v[108:109], v[128:129]
	v_mov_b64_e32 v[110:111], v[130:131]
	v_mov_b64_e32 v[88:89], v[132:133]
	v_mov_b64_e32 v[66:67], v[134:135]
	v_mov_b64_e32 v[102:103], v[136:137]
	v_mov_b64_e32 v[92:93], v[138:139]
	v_add_u32_e32 v140, s79, v36
	v_cmp_gt_i32_e32 vcc, 0x4000, v140
	s_and_saveexec_b64 s[12:13], vcc
	s_cbranch_execz .Lrn_pf_skip1
	v_ashrrev_i32_e32 v141, 31, v140
	v_lshlrev_b64 v[142:143], 13, v[140:141]
	v_lshl_add_u64 v[142:143], v[34:35], 0, v[142:143]
	v_lshlrev_b64 v[144:145], 12, v[140:141]
	v_lshl_add_u64 v[146:147], v[142:143], 0, v[0:1]
	v_lshl_add_u64 v[144:145], v[38:39], 0, v[144:145]
	global_load_dwordx4 v[160:163], v[146:147], off nt
	global_load_dwordx4 v[164:167], v[146:147], off offset:1024 nt
	global_load_dwordx4 v[168:171], v[146:147], off offset:2048 nt
	global_load_dwordx4 v[172:175], v[146:147], off offset:3072 nt
	global_load_dwordx2 v[124:125], v[144:145], off nt
	v_lshl_add_u64 v[146:147], v[142:143], 0, v[42:43]
	global_load_dwordx4 v[176:179], v[146:147], off nt
	v_lshl_add_u64 v[146:147], v[142:143], 0, v[44:45]
	global_load_dwordx4 v[180:183], v[146:147], off nt
	v_lshl_add_u64 v[146:147], v[142:143], 0, v[46:47]
	global_load_dwordx4 v[184:187], v[146:147], off nt
	v_lshl_add_u64 v[146:147], v[142:143], 0, v[48:49]
	global_load_dwordx4 v[188:191], v[146:147], off nt
	global_load_dwordx2 v[126:127], v[144:145], off offset:512 nt
	global_load_dwordx2 v[128:129], v[144:145], off offset:1024 nt
	global_load_dwordx2 v[130:131], v[144:145], off offset:1536 nt
	global_load_dwordx2 v[132:133], v[144:145], off offset:2048 nt
	global_load_dwordx2 v[134:135], v[144:145], off offset:2560 nt
	global_load_dwordx2 v[136:137], v[144:145], off offset:3072 nt
	global_load_dwordx2 v[138:139], v[144:145], off offset:3584 nt
; DI float bflo(unsigned u) { return __uint_as_float(u << 16); }
; DI float bfhi(unsigned u) { return __uint_as_float(u & 0xffff0000u); }
; DI float wave_sum(float v) { v += __shfl_xor(v, 32); v += __shfl_xor(v, 16); v += __shfl_xor(v, 8); v += __shfl_xor(v, 4); v += __shfl_xor(v, 2); v += __shfl_xor(v, 1); return v; }
; DI void rownorm_phase(const Params& P, const float* xin, const bf16_t* yin, float* xout, bf16_t* hout, int lg, int gate_idx, const float* w_post,
;                       int lh, int scale_idx, int shift_idx, const float* w_pre, char* smem) {
;     ...
;     if (yin) {
;       f32x4 yv[8]; float ss = 0.f;
; #pragma unroll
;       for (int j = 0; j < 8; ++j) { const u32x2 yb = __builtin_nontemporal_load((const u32x2*)(yin + (size_t)row * 2048 + (j * 64 + lane) * 4)); yv[j] = (f32x4){bflo(yb.x), bfhi(yb.x), bflo(yb.y), bfhi(yb.y)};
;         ss += yv[j].x * yv[j].x + yv[j].y * yv[j].y + yv[j].z * yv[j].z + yv[j].w * yv[j].w; }
;       ss = wave_sum(ss); const float r = rsqrtf(ss * (1.f / 2048.f) + EPS);
; #pragma unroll
;       for (int j = 0; j < 8; ++j) { const f32x4 a = *(const f32x4*)(A1 + (j * 64 + lane) * 4); xv[j] += a * (yv[j] * r); }
.Lrn_pf_skip1:
	s_or_b64 exec, exec, s[12:13]
	v_add_u32_e32 v36, s79, v36
	v_lshlrev_b32_e32 v70, 16, v62
	v_and_b32_e32 v71, 0xffff0000, v62
	v_lshlrev_b32_e32 v72, 16, v63
	v_and_b32_e32 v73, 0xffff0000, v63
	v_mul_f32_e32 v37, v71, v71
	v_fmac_f32_e32 v37, v70, v70
	v_fmac_f32_e32 v37, v72, v72
	v_fmac_f32_e32 v37, v73, v73
	v_lshlrev_b32_e32 v74, 16, v106
	v_and_b32_e32 v75, 0xffff0000, v106
	v_lshlrev_b32_e32 v76, 16, v107
	v_and_b32_e32 v77, 0xffff0000, v107
	v_mul_f32_e32 v43, v75, v75
	v_fmac_f32_e32 v43, v74, v74
	v_fmac_f32_e32 v43, v76, v76
	v_fmac_f32_e32 v43, v77, v77
	v_add_f32_e32 v37, v37, v43
	v_lshlrev_b32_e32 v78, 16, v108
	v_and_b32_e32 v79, 0xffff0000, v108
	v_lshlrev_b32_e32 v80, 16, v109
	v_and_b32_e32 v81, 0xffff0000, v109
	v_mul_f32_e32 v43, v79, v79
	v_fmac_f32_e32 v43, v78, v78
	v_fmac_f32_e32 v43, v80, v80
	v_fmac_f32_e32 v43, v81, v81
	v_add_f32_e32 v37, v37, v43
	v_lshlrev_b32_e32 v64, 16, v88
	v_and_b32_e32 v83, 0xffff0000, v110
	v_lshlrev_b32_e32 v82, 16, v110
	v_lshlrev_b32_e32 v84, 16, v111
	v_and_b32_e32 v85, 0xffff0000, v111
	v_mul_f32_e32 v43, v83, v83
	v_and_b32_e32 v63, 0xffff0000, v66
	v_and_b32_e32 v62, 0xffff0000, v88
	v_fmac_f32_e32 v43, v82, v82
	v_lshlrev_b32_e32 v65, 16, v66
	v_lshlrev_b32_e32 v68, 16, v89
	v_and_b32_e32 v66, 0xffff0000, v89
	v_pk_mul_f32 v[88:89], v[62:63], v[62:63]
	v_fmac_f32_e32 v43, v84, v84
	v_lshlrev_b32_e32 v69, 16, v67
	v_pk_fma_f32 v[88:89], v[64:65], v[64:65], v[88:89]
	v_fmac_f32_e32 v43, v85, v85
	v_and_b32_e32 v67, 0xffff0000, v67
	v_pk_fma_f32 v[88:89], v[68:69], v[68:69], v[88:89]
	v_add_f32_e32 v37, v37, v43
	v_pk_fma_f32 v[88:89], v[66:67], v[66:67], v[88:89]
	v_lshlrev_b32_e32 v87, 16, v92
	v_add_f32_e32 v37, v37, v88
	v_add_f32_e32 v37, v37, v89
	v_and_b32_e32 v89, 0xffff0000, v92
	v_and_b32_e32 v88, 0xffff0000, v102
	v_lshlrev_b32_e32 v86, 16, v102
	v_lshlrev_b32_e32 v90, 16, v103
	v_and_b32_e32 v92, 0xffff0000, v103
	v_pk_mul_f32 v[102:103], v[88:89], v[88:89]
	v_lshlrev_b32_e32 v91, 16, v93
	v_pk_fma_f32 v[102:103], v[86:87], v[86:87], v[102:103]
	v_and_b32_e32 v93, 0xffff0000, v93
	v_pk_fma_f32 v[102:103], v[90:91], v[90:91], v[102:103]
	s_nop 0
	v_pk_fma_f32 v[102:103], v[92:93], v[92:93], v[102:103]
	s_nop 0
	v_add_f32_e32 v37, v37, v102
	v_add_f32_e32 v37, v37, v103
	v_mov_b32_e32 v120, v37
	v_mov_b32_e32 v121, v37
	s_nop 1
	v_permlane32_swap_b32_e32 v120, v121
	ds_read_b128 v[102:105], v95
	s_waitcnt lgkmcnt(0)
	v_add_f32_e32 v37, v120, v121
	v_mov_b32_e32 v120, v37
	v_mov_b32_e32 v121, v37
	s_nop 1
	v_permlane16_swap_b32_e32 v120, v121
	s_waitcnt lgkmcnt(0)
	v_add_f32_e32 v37, v120, v121
	s_nop 1
	s_waitcnt lgkmcnt(0)
	v_add_f32_dpp v37, v37, v37 row_ror:8 row_mask:0xf bank_mask:0xf
	s_nop 1
	v_mov_b32_dpp v120, v37 row_ror:4 row_mask:0xf bank_mask:0xa
	v_mov_b32_dpp v120, v37 row_ror:12 row_mask:0xf bank_mask:0x5
	s_waitcnt lgkmcnt(0)
	v_add_f32_e32 v37, v37, v120
	s_nop 1
	s_waitcnt lgkmcnt(0)
	v_add_f32_dpp v37, v37, v37 quad_perm:[2,3,0,1] row_mask:0xf bank_mask:0xf
	s_nop 1
	s_waitcnt lgkmcnt(0)
	v_add_f32_dpp v37, v37, v37 quad_perm:[1,0,3,2] row_mask:0xf bank_mask:0xf
	v_fmamk_f32 v37, v37, 0x3a000000, v245
	v_cmp_gt_f32_e32 vcc, s84, v37
	v_mul_f32_e32 v43, 0x4b800000, v37
	s_nop 0
	v_cndmask_b32_e32 v37, v37, v43, vcc
	v_rsq_f32_e32 v37, v37
	s_nop 0
	v_mul_f32_e32 v43, 0x45800000, v37
	v_cndmask_b32_e32 v94, v37, v43, vcc
	v_pk_mul_f32 v[70:71], v[70:71], v[94:95] op_sel_hi:[1,0]
	v_pk_mul_f32 v[72:73], v[72:73], v[94:95] op_sel_hi:[1,0]
	v_pk_fma_f32 v[30:31], v[102:103], v[70:71], v[30:31]
	v_pk_fma_f32 v[32:33], v[104:105], v[72:73], v[32:33]
	ds_read_b128 v[70:73], v95 offset:1024
	v_pk_mul_f32 v[74:75], v[74:75], v[94:95] op_sel_hi:[1,0]
	v_pk_mul_f32 v[76:77], v[76:77], v[94:95] op_sel_hi:[1,0]
	v_mul_f32_e32 v37, v31, v31
	v_fmac_f32_e32 v37, v30, v30
	s_waitcnt lgkmcnt(0)
	v_pk_fma_f32 v[28:29], v[72:73], v[76:77], v[28:29]
	v_pk_fma_f32 v[26:27], v[70:71], v[74:75], v[26:27]
	ds_read_b128 v[70:73], v95 offset:2048
	v_pk_mul_f32 v[74:75], v[78:79], v[94:95] op_sel_hi:[1,0]
	v_pk_mul_f32 v[76:77], v[80:81], v[94:95] op_sel_hi:[1,0]
	v_mul_f32_e32 v43, v27, v27
	v_fmac_f32_e32 v43, v26, v26
	s_waitcnt lgkmcnt(0)
	v_pk_fma_f32 v[24:25], v[72:73], v[76:77], v[24:25]
	v_pk_fma_f32 v[22:23], v[70:71], v[74:75], v[22:23]
	ds_read_b128 v[70:73], v95 offset:3072
	v_pk_mul_f32 v[74:75], v[82:83], v[94:95] op_sel_hi:[1,0]
	v_pk_mul_f32 v[76:77], v[84:85], v[94:95] op_sel_hi:[1,0]
	v_fmac_f32_e32 v37, v32, v32
	v_fmac_f32_e32 v43, v28, v28
	s_waitcnt lgkmcnt(0)
	v_pk_fma_f32 v[20:21], v[72:73], v[76:77], v[20:21]
	v_pk_fma_f32 v[18:19], v[70:71], v[74:75], v[18:19]
	ds_read_b128 v[70:73], v95 offset:4096
	v_mov_b32_e32 v74, v64
	v_mov_b32_e32 v75, v62
	v_mov_b32_e32 v76, v68
	v_mov_b32_e32 v77, v66
	v_pk_mul_f32 v[74:75], v[74:75], v[94:95] op_sel_hi:[1,0]
	v_pk_mul_f32 v[76:77], v[76:77], v[94:95] op_sel_hi:[1,0]
	s_waitcnt lgkmcnt(0)
	v_pk_fma_f32 v[14:15], v[70:71], v[74:75], v[14:15]
	v_pk_fma_f32 v[16:17], v[72:73], v[76:77], v[16:17]
	ds_read_b128 v[70:73], v95 offset:5120
	v_mov_b32_e32 v62, v65
	v_mov_b32_e32 v66, v69
	v_pk_mul_f32 v[62:63], v[62:63], v[94:95] op_sel_hi:[1,0]
	v_pk_mul_f32 v[64:65], v[66:67], v[94:95] op_sel_hi:[1,0]
	s_waitcnt lgkmcnt(0)
	v_pk_fma_f32 v[10:11], v[70:71], v[62:63], v[10:11]
	v_pk_fma_f32 v[12:13], v[72:73], v[64:65], v[12:13]
	ds_read_b128 v[62:65], v95 offset:6144
	v_mov_b32_e32 v66, v86
	v_mov_b32_e32 v67, v88
	v_mov_b32_e32 v68, v90
	v_mov_b32_e32 v69, v92
	v_pk_mul_f32 v[66:67], v[66:67], v[94:95] op_sel_hi:[1,0]
	v_pk_mul_f32 v[68:69], v[68:69], v[94:95] op_sel_hi:[1,0]
	s_waitcnt lgkmcnt(0)
; DI unsigned pack2(float lo, float hi) { f32x2 v = {lo, hi}; bf2_t b = __builtin_convertvector(v, bf2_t); return __builtin_bit_cast(unsigned, b); }
; DI float wave_sum(float v) { v += __shfl_xor(v, 32); v += __shfl_xor(v, 16); v += __shfl_xor(v, 8); v += __shfl_xor(v, 4); v += __shfl_xor(v, 2); v += __shfl_xor(v, 1); return v; }
; DI void rownorm_phase(const Params& P, const float* xin, const bf16_t* yin, float* xout, bf16_t* hout, int lg, int gate_idx, const float* w_post,
;                       int lh, int scale_idx, int shift_idx, const float* w_pre, char* smem) {
;     ...
;     if (yin || xout != xin) {
; #pragma unroll
;       for (int j = 0; j < 8; ++j) __builtin_nontemporal_store(xv[j], (f32x4*)(xout + (size_t)row * 2048 + (j * 64 + lane) * 4));
;     }
;     if (hout) {
;       float ss = 0.f;
; #pragma unroll
;       for (int j = 0; j < 8; ++j) ss += xv[j].x * xv[j].x + xv[j].y * xv[j].y + xv[j].z * xv[j].z + xv[j].w * xv[j].w;
;       ss = wave_sum(ss); const float r = rsqrtf(ss * (1.f / 2048.f) + EPS);
; #pragma unroll
;       for (int j = 0; j < 8; ++j) { const f32x4 a = *(const f32x4*)(A2 + (j * 64 + lane) * 4), b = *(const f32x4*)(B2 + (j * 64 + lane) * 4);
;         const f32x4 hv = xv[j] * r * a + b; u32x2 pk = {pack2(hv.x, hv.y), pack2(hv.z, hv.w)};
;         *(u32x2*)(hout + (size_t)row * 2048 + (j * 64 + lane) * 4) = pk; }
	v_pk_fma_f32 v[6:7], v[62:63], v[66:67], v[6:7]
	v_pk_fma_f32 v[8:9], v[64:65], v[68:69], v[8:9]
	ds_read_b128 v[62:65], v95 offset:7168
	v_fmac_f32_e32 v37, v33, v33
	v_fmac_f32_e32 v43, v29, v29
	v_add_f32_e32 v37, v37, v43
	v_mul_f32_e32 v43, v23, v23
	v_fmac_f32_e32 v43, v22, v22
	v_mov_b32_e32 v88, v87
	v_mov_b32_e32 v92, v91
	v_fmac_f32_e32 v43, v24, v24
	v_pk_mul_f32 v[66:67], v[88:89], v[94:95] op_sel_hi:[1,0]
	v_pk_mul_f32 v[68:69], v[92:93], v[94:95] op_sel_hi:[1,0]
	v_fmac_f32_e32 v43, v25, v25
	s_waitcnt lgkmcnt(0)
	v_pk_fma_f32 v[4:5], v[64:65], v[68:69], v[4:5]
	v_pk_fma_f32 v[2:3], v[62:63], v[66:67], v[2:3]
	global_store_dwordx4 v[52:53], v[30:33], off nt
	global_store_dwordx4 v[52:53], v[26:29], off offset:1024 nt
	global_store_dwordx4 v[52:53], v[22:25], off offset:2048 nt
	global_store_dwordx4 v[52:53], v[18:21], off offset:3072 nt
	global_store_dwordx4 v[54:55], v[14:17], off nt
	global_store_dwordx4 v[56:57], v[10:13], off nt
	global_store_dwordx4 v[58:59], v[6:9], off nt
	global_store_dwordx4 v[60:61], v[2:5], off nt
	v_add_f32_e32 v37, v43, v37
	v_mul_f32_e32 v43, v19, v19
	v_mov_b32_e32 v54, v11
	v_mov_b32_e32 v55, v15
	v_fmac_f32_e32 v43, v18, v18
	v_mov_b32_e32 v52, v10
	v_mov_b32_e32 v53, v14
	v_pk_mul_f32 v[54:55], v[54:55], v[54:55]
	v_fmac_f32_e32 v43, v20, v20
	v_pk_fma_f32 v[52:53], v[52:53], v[52:53], v[54:55]
	v_mov_b32_e32 v54, v12
	v_mov_b32_e32 v55, v16
	v_fmac_f32_e32 v43, v21, v21
	v_pk_fma_f32 v[52:53], v[54:55], v[54:55], v[52:53]
	v_mov_b32_e32 v54, v13
	v_mov_b32_e32 v55, v17
	v_add_f32_e32 v37, v43, v37
	v_pk_fma_f32 v[52:53], v[54:55], v[54:55], v[52:53]
	v_mov_b32_e32 v54, v3
	v_add_f32_e32 v37, v53, v37
	v_mov_b32_e32 v55, v7
	v_add_f32_e32 v37, v52, v37
	v_mov_b32_e32 v52, v2
	v_mov_b32_e32 v53, v6
	v_pk_mul_f32 v[54:55], v[54:55], v[54:55]
	s_nop 0
	v_pk_fma_f32 v[52:53], v[52:53], v[52:53], v[54:55]
	v_mov_b32_e32 v54, v4
	v_mov_b32_e32 v55, v8
	v_pk_fma_f32 v[52:53], v[54:55], v[54:55], v[52:53]
	v_mov_b32_e32 v54, v5
	v_mov_b32_e32 v55, v9
	v_pk_fma_f32 v[52:53], v[54:55], v[54:55], v[52:53]
	ds_read_b128 v[54:57], v95 offset:8192
	ds_read_b128 v[58:61], v95 offset:16384
	v_add_f32_e32 v37, v53, v37
	v_add_f32_e32 v37, v52, v37
	v_mov_b32_e32 v120, v37
	v_mov_b32_e32 v121, v37
	s_nop 1
	v_permlane32_swap_b32_e32 v120, v121
	s_waitcnt lgkmcnt(0)
	v_add_f32_e32 v37, v120, v121
	v_mov_b32_e32 v120, v37
	v_mov_b32_e32 v121, v37
	s_nop 1
	v_permlane16_swap_b32_e32 v120, v121
	s_waitcnt lgkmcnt(0)
	v_add_f32_e32 v37, v120, v121
	s_nop 1
	s_waitcnt lgkmcnt(0)
	v_add_f32_dpp v37, v37, v37 row_ror:8 row_mask:0xf bank_mask:0xf
	s_nop 1
	v_mov_b32_dpp v120, v37 row_ror:4 row_mask:0xf bank_mask:0xa
	v_mov_b32_dpp v120, v37 row_ror:12 row_mask:0xf bank_mask:0x5
	s_waitcnt lgkmcnt(0)
	v_add_f32_e32 v37, v37, v120
	s_nop 1
	s_waitcnt lgkmcnt(0)
	v_add_f32_dpp v37, v37, v37 quad_perm:[2,3,0,1] row_mask:0xf bank_mask:0xf
	s_nop 1
	s_waitcnt lgkmcnt(0)
	v_add_f32_dpp v37, v37, v37 quad_perm:[1,0,3,2] row_mask:0xf bank_mask:0xf
	v_fmamk_f32 v37, v37, 0x3a000000, v245
	v_cmp_gt_f32_e32 vcc, s84, v37
	v_mul_f32_e32 v43, 0x4b800000, v37
	s_nop 0
	v_cndmask_b32_e32 v37, v37, v43, vcc
	v_rsq_f32_e32 v37, v37
	s_nop 0
	v_mul_f32_e32 v43, 0x45800000, v37
	v_cndmask_b32_e32 v52, v37, v43, vcc
	v_pk_mul_f32 v[30:31], v[30:31], v[52:53] op_sel_hi:[1,0]
	v_pk_mul_f32 v[32:33], v[32:33], v[52:53] op_sel_hi:[1,0]
	v_pk_fma_f32 v[30:31], v[54:55], v[30:31], v[58:59]
	v_pk_fma_f32 v[32:33], v[56:57], v[32:33], v[60:61]
	v_cvt_pk_bf16_f32 v54, v30, v31
	v_cvt_pk_bf16_f32 v55, v32, v33
	v_lshl_add_u64 v[30:31], v[40:41], 0, v[50:51]
	global_store_dwordx2 v[30:31], v[54:55], off
	ds_read_b128 v[54:57], v95 offset:9216
	ds_read_b128 v[58:61], v95 offset:17408
	v_pk_mul_f32 v[26:27], v[26:27], v[52:53] op_sel_hi:[1,0]
	v_pk_mul_f32 v[28:29], v[28:29], v[52:53] op_sel_hi:[1,0]
	v_pk_mul_f32 v[22:23], v[22:23], v[52:53] op_sel_hi:[1,0]
	v_pk_mul_f32 v[24:25], v[24:25], v[52:53] op_sel_hi:[1,0]
	s_waitcnt lgkmcnt(0)
	v_pk_fma_f32 v[28:29], v[56:57], v[28:29], v[60:61]
	v_pk_fma_f32 v[26:27], v[54:55], v[26:27], v[58:59]
	v_pk_mul_f32 v[18:19], v[18:19], v[52:53] op_sel_hi:[1,0]
	v_cvt_pk_bf16_f32 v26, v26, v27
	v_cvt_pk_bf16_f32 v27, v28, v29
	global_store_dwordx2 v[30:31], v[26:27], off offset:512
	ds_read_b128 v[26:29], v95 offset:10240
	ds_read_b128 v[54:57], v95 offset:18432
	v_pk_mul_f32 v[20:21], v[20:21], v[52:53] op_sel_hi:[1,0]
	v_pk_mul_f32 v[14:15], v[14:15], v[52:53] op_sel_hi:[1,0]
	v_pk_mul_f32 v[16:17], v[16:17], v[52:53] op_sel_hi:[1,0]
	v_pk_mul_f32 v[10:11], v[10:11], v[52:53] op_sel_hi:[1,0]
	s_waitcnt lgkmcnt(0)
	v_pk_fma_f32 v[24:25], v[28:29], v[24:25], v[56:57]
	v_pk_fma_f32 v[22:23], v[26:27], v[22:23], v[54:55]
	v_pk_mul_f32 v[12:13], v[12:13], v[52:53] op_sel_hi:[1,0]
	v_cvt_pk_bf16_f32 v22, v22, v23
	v_cvt_pk_bf16_f32 v23, v24, v25
	global_store_dwordx2 v[30:31], v[22:23], off offset:1024
	ds_read_b128 v[22:25], v95 offset:11264
	ds_read_b128 v[26:29], v95 offset:19456
	v_pk_mul_f32 v[6:7], v[6:7], v[52:53] op_sel_hi:[1,0]
	v_pk_mul_f32 v[8:9], v[8:9], v[52:53] op_sel_hi:[1,0]
	v_pk_mul_f32 v[2:3], v[2:3], v[52:53] op_sel_hi:[1,0]
	v_pk_mul_f32 v[4:5], v[4:5], v[52:53] op_sel_hi:[1,0]
	s_waitcnt lgkmcnt(0)
	v_pk_fma_f32 v[20:21], v[24:25], v[20:21], v[28:29]
	v_pk_fma_f32 v[18:19], v[22:23], v[18:19], v[26:27]
	v_cmp_lt_i32_e32 vcc, s10, v36
	v_cvt_pk_bf16_f32 v18, v18, v19
	v_cvt_pk_bf16_f32 v19, v20, v21
	global_store_dwordx2 v[30:31], v[18:19], off offset:1536
	ds_read_b128 v[18:21], v95 offset:12288
	ds_read_b128 v[22:25], v95 offset:20480
	s_or_b64 s[8:9], vcc, s[8:9]
	s_waitcnt lgkmcnt(0)
	v_pk_fma_f32 v[16:17], v[20:21], v[16:17], v[24:25]
	v_pk_fma_f32 v[14:15], v[18:19], v[14:15], v[22:23]
	s_nop 0
	v_cvt_pk_bf16_f32 v14, v14, v15
	v_cvt_pk_bf16_f32 v15, v16, v17
	global_store_dwordx2 v[30:31], v[14:15], off offset:2048
	ds_read_b128 v[14:17], v95 offset:13312
	ds_read_b128 v[18:21], v95 offset:21504
	s_waitcnt lgkmcnt(0)
	v_pk_fma_f32 v[12:13], v[16:17], v[12:13], v[20:21]
	v_pk_fma_f32 v[10:11], v[14:15], v[10:11], v[18:19]
	s_nop 0
	v_cvt_pk_bf16_f32 v10, v10, v11
	v_cvt_pk_bf16_f32 v11, v12, v13
	global_store_dwordx2 v[30:31], v[10:11], off offset:2560
	ds_read_b128 v[10:13], v95 offset:14336
	ds_read_b128 v[14:17], v95 offset:22528
	s_waitcnt lgkmcnt(0)
	v_pk_fma_f32 v[8:9], v[12:13], v[8:9], v[16:17]
	v_pk_fma_f32 v[6:7], v[10:11], v[6:7], v[14:15]
	s_nop 0
	v_cvt_pk_bf16_f32 v6, v6, v7
	v_cvt_pk_bf16_f32 v7, v8, v9
	global_store_dwordx2 v[30:31], v[6:7], off offset:3072
	ds_read_b128 v[6:9], v95 offset:15360
	ds_read_b128 v[10:13], v95 offset:23552
	s_waitcnt lgkmcnt(0)
	v_pk_fma_f32 v[4:5], v[8:9], v[4:5], v[12:13]
	v_pk_fma_f32 v[2:3], v[6:7], v[2:3], v[10:11]
	s_nop 0
	v_cvt_pk_bf16_f32 v2, v2, v3
	v_cvt_pk_bf16_f32 v3, v4, v5
	global_store_dwordx2 v[30:31], v[2:3], off offset:3584
	s_andn2_b64 exec, exec, s[8:9]
	s_cbranch_execnz .LBB0_889

; DI float bflo(unsigned u) { return __uint_as_float(u << 16); }
; DI float bfhi(unsigned u) { return __uint_as_float(u & 0xffff0000u); }
; DI void rownorm_phase(const Params& P, const float* xin, const bf16_t* yin, float* xout, bf16_t* hout, int lg, int gate_idx, const float* w_post,
;                       int lh, int scale_idx, int shift_idx, const float* w_pre, char* smem) {
;     ...
;   for (int row = blockIdx.x * 8 + w; row < S_; row += gridDim.x * 8) {
;     f32x4 xv[8];
; #pragma unroll
;     for (int j = 0; j < 8; ++j) xv[j] = __builtin_nontemporal_load((const f32x4*)(xin + (size_t)row * 2048 + (j * 64 + lane) * 4));
;     if (yin) {
;       f32x4 yv[8]; float ss = 0.f;
; #pragma unroll
;       for (int j = 0; j < 8; ++j) { const u32x2 yb = __builtin_nontemporal_load((const u32x2*)(yin + (size_t)row * 2048 + (j * 64 + lane) * 4)); yv[j] = (f32x4){bflo(yb.x), bfhi(yb.x), bflo(yb.y), bfhi(yb.y)};
.LBB0_1234:
	s_or_b64 exec, exec, s[0:1]
	v_ashrrev_i32_e32 v0, 6, v2
	v_readlane_b32 s0, v254, 3
	s_waitcnt lgkmcnt(0)
	s_barrier
	v_add_u32_e32 v36, s0, v0
	s_movk_i32 s0, 0x4000
	v_cmp_gt_i32_e32 vcc, s0, v36
	s_and_saveexec_b64 s[0:1], vcc
	s_movk_i32 s4, 0x3fff
	s_cbranch_execz .LBB0_1237
	s_waitcnt vmcnt(0)
	v_and_b32_e32 v5, 64, v239
	v_xor_b32_e32 v3, 32, v239
	v_add_u32_e32 v5, 64, v5
	v_cmp_lt_i32_e32 vcc, v3, v5
	v_and_b32_e32 v0, 63, v2
	v_lshlrev_b32_e32 v2, 2, v0
	v_cndmask_b32_e32 v3, v239, v3, vcc
	v_lshlrev_b32_e32 v96, 2, v3
	v_xor_b32_e32 v3, 16, v239
	v_cmp_lt_i32_e32 vcc, v3, v5
	v_lshlrev_b32_e32 v95, 4, v0
	v_or_b32_e32 v4, 0x400, v2
	v_cndmask_b32_e32 v3, v239, v3, vcc
	v_lshlrev_b32_e32 v97, 2, v3
	v_xor_b32_e32 v3, 8, v239
	v_cmp_lt_i32_e32 vcc, v3, v5
	v_or_b32_e32 v6, 0x500, v2
	v_or_b32_e32 v8, 0x600, v2
	v_cndmask_b32_e32 v3, v239, v3, vcc
	v_lshlrev_b32_e32 v98, 2, v3
	v_xor_b32_e32 v3, 4, v239
	v_cmp_lt_i32_e32 vcc, v3, v5
	v_or_b32_e32 v10, 0x700, v2
	v_lshlrev_b32_e32 v0, 3, v0
	v_cndmask_b32_e32 v3, v239, v3, vcc
	v_lshlrev_b32_e32 v99, 2, v3
	v_xor_b32_e32 v3, 2, v239
	v_cmp_lt_i32_e32 vcc, v3, v5
	v_lshl_add_u64 v[38:39], s[46:47], 0, v[0:1]
	v_lshl_add_u64 v[40:41], s[60:61], 0, v[0:1]
	v_cndmask_b32_e32 v3, v239, v3, vcc
	v_lshlrev_b32_e32 v100, 2, v3
	v_xor_b32_e32 v3, 1, v239
	v_cmp_lt_i32_e32 vcc, v3, v5
	s_mov_b64 s[2:3], 0
	v_lshlrev_b32_e32 v0, 2, v2
	v_cndmask_b32_e32 v3, v239, v3, vcc
	v_lshlrev_b32_e32 v101, 2, v3
	v_lshlrev_b32_e32 v42, 2, v4
	v_lshlrev_b32_e32 v44, 2, v6
	v_lshlrev_b32_e32 v46, 2, v8
	v_lshlrev_b32_e32 v48, 2, v10
	v_mov_b32_e32 v43, v1
	v_mov_b32_e32 v45, v1
	v_mov_b32_e32 v47, v1
	v_mov_b32_e32 v49, v1
	v_ashrrev_i32_e32 v141, 31, v36
	v_mov_b32_e32 v140, v36
	v_lshlrev_b64 v[142:143], 13, v[140:141]
	v_lshl_add_u64 v[142:143], v[34:35], 0, v[142:143]
	v_lshlrev_b64 v[144:145], 12, v[140:141]
	v_lshl_add_u64 v[146:147], v[142:143], 0, v[0:1]
	v_lshl_add_u64 v[144:145], v[38:39], 0, v[144:145]
	global_load_dwordx4 v[160:163], v[146:147], off nt
	global_load_dwordx4 v[164:167], v[146:147], off offset:1024 nt
	global_load_dwordx4 v[168:171], v[146:147], off offset:2048 nt
	global_load_dwordx4 v[172:175], v[146:147], off offset:3072 nt
	global_load_dwordx2 v[124:125], v[144:145], off nt
	v_lshl_add_u64 v[146:147], v[142:143], 0, v[42:43]
	global_load_dwordx4 v[176:179], v[146:147], off nt
	v_lshl_add_u64 v[146:147], v[142:143], 0, v[44:45]
	global_load_dwordx4 v[180:183], v[146:147], off nt
	v_lshl_add_u64 v[146:147], v[142:143], 0, v[46:47]
	global_load_dwordx4 v[184:187], v[146:147], off nt
	v_lshl_add_u64 v[146:147], v[142:143], 0, v[48:49]
	global_load_dwordx4 v[188:191], v[146:147], off nt
	global_load_dwordx2 v[126:127], v[144:145], off offset:512 nt
	global_load_dwordx2 v[128:129], v[144:145], off offset:1024 nt
	global_load_dwordx2 v[130:131], v[144:145], off offset:1536 nt
	global_load_dwordx2 v[132:133], v[144:145], off offset:2048 nt
	global_load_dwordx2 v[134:135], v[144:145], off offset:2560 nt
	global_load_dwordx2 v[136:137], v[144:145], off offset:3072 nt
	global_load_dwordx2 v[138:139], v[144:145], off offset:3584 nt

; DI float bflo(unsigned u) { return __uint_as_float(u << 16); }
; DI float bfhi(unsigned u) { return __uint_as_float(u & 0xffff0000u); }
; DI float wave_sum(float v) { v += __shfl_xor(v, 32); v += __shfl_xor(v, 16); v += __shfl_xor(v, 8); v += __shfl_xor(v, 4); v += __shfl_xor(v, 2); v += __shfl_xor(v, 1); return v; }
; DI void rownorm_phase(const Params& P, const float* xin, const bf16_t* yin, float* xout, bf16_t* hout, int lg, int gate_idx, const float* w_post,
;                       int lh, int scale_idx, int shift_idx, const float* w_pre, char* smem) {
;     ...
;     if (yin) {
;       f32x4 yv[8]; float ss = 0.f;
; #pragma unroll
;       for (int j = 0; j < 8; ++j) { const u32x2 yb = __builtin_nontemporal_load((const u32x2*)(yin + (size_t)row * 2048 + (j * 64 + lane) * 4)); yv[j] = (f32x4){bflo(yb.x), bfhi(yb.x), bflo(yb.y), bfhi(yb.y)};
;         ss += yv[j].x * yv[j].x + yv[j].y * yv[j].y + yv[j].z * yv[j].z + yv[j].w * yv[j].w; }
;       ss = wave_sum(ss); const float r = rsqrtf(ss * (1.f / 2048.f) + EPS);
; #pragma unroll
;       for (int j = 0; j < 8; ++j) { const f32x4 a = *(const f32x4*)(A1 + (j * 64 + lane) * 4); xv[j] += a * (yv[j] * r); }
.Lrn_pf_skip2:
	s_or_b64 exec, exec, s[12:13]
	v_add_u32_e32 v36, s79, v36
	v_lshlrev_b32_e32 v70, 16, v62
	v_and_b32_e32 v71, 0xffff0000, v62
	v_lshlrev_b32_e32 v72, 16, v63
	v_and_b32_e32 v73, 0xffff0000, v63
	v_mul_f32_e32 v37, v71, v71
	v_fmac_f32_e32 v37, v70, v70
	v_fmac_f32_e32 v37, v72, v72
	v_fmac_f32_e32 v37, v73, v73
	v_lshlrev_b32_e32 v74, 16, v106
	v_and_b32_e32 v75, 0xffff0000, v106
	v_lshlrev_b32_e32 v76, 16, v107
	v_and_b32_e32 v77, 0xffff0000, v107
	v_mul_f32_e32 v43, v75, v75
	v_fmac_f32_e32 v43, v74, v74
	v_fmac_f32_e32 v43, v76, v76
	v_fmac_f32_e32 v43, v77, v77
	v_add_f32_e32 v37, v37, v43
	v_lshlrev_b32_e32 v78, 16, v108
	v_and_b32_e32 v79, 0xffff0000, v108
	v_lshlrev_b32_e32 v80, 16, v109
	v_and_b32_e32 v81, 0xffff0000, v109
	v_mul_f32_e32 v43, v79, v79
	v_fmac_f32_e32 v43, v78, v78
	v_fmac_f32_e32 v43, v80, v80
	v_fmac_f32_e32 v43, v81, v81
	v_add_f32_e32 v37, v37, v43
	v_lshlrev_b32_e32 v64, 16, v88
	v_and_b32_e32 v83, 0xffff0000, v110
	v_lshlrev_b32_e32 v82, 16, v110
	v_lshlrev_b32_e32 v84, 16, v111
	v_and_b32_e32 v85, 0xffff0000, v111
	v_mul_f32_e32 v43, v83, v83
	v_and_b32_e32 v63, 0xffff0000, v66
	v_and_b32_e32 v62, 0xffff0000, v88
	v_fmac_f32_e32 v43, v82, v82
	v_lshlrev_b32_e32 v65, 16, v66
	v_lshlrev_b32_e32 v68, 16, v89
	v_and_b32_e32 v66, 0xffff0000, v89
	v_pk_mul_f32 v[88:89], v[62:63], v[62:63]
	v_fmac_f32_e32 v43, v84, v84
	v_lshlrev_b32_e32 v69, 16, v67
	v_pk_fma_f32 v[88:89], v[64:65], v[64:65], v[88:89]
	v_fmac_f32_e32 v43, v85, v85
	v_and_b32_e32 v67, 0xffff0000, v67
	v_pk_fma_f32 v[88:89], v[68:69], v[68:69], v[88:89]
	v_add_f32_e32 v37, v37, v43
	v_pk_fma_f32 v[88:89], v[66:67], v[66:67], v[88:89]
	v_lshlrev_b32_e32 v87, 16, v92
	v_add_f32_e32 v37, v37, v88
	v_add_f32_e32 v37, v37, v89
	v_and_b32_e32 v89, 0xffff0000, v92
	v_and_b32_e32 v88, 0xffff0000, v102
	v_lshlrev_b32_e32 v86, 16, v102
	v_lshlrev_b32_e32 v90, 16, v103
	v_and_b32_e32 v92, 0xffff0000, v103
	v_pk_mul_f32 v[102:103], v[88:89], v[88:89]
	v_lshlrev_b32_e32 v91, 16, v93
	v_pk_fma_f32 v[102:103], v[86:87], v[86:87], v[102:103]
	v_and_b32_e32 v93, 0xffff0000, v93
	v_pk_fma_f32 v[102:103], v[90:91], v[90:91], v[102:103]
	s_nop 0
	v_pk_fma_f32 v[102:103], v[92:93], v[92:93], v[102:103]
	s_nop 0
	v_add_f32_e32 v37, v37, v102
	v_add_f32_e32 v37, v37, v103
	v_mov_b32_e32 v120, v37
	v_mov_b32_e32 v121, v37
	s_nop 1
	v_permlane32_swap_b32_e32 v120, v121
	ds_read_b128 v[102:105], v95
	s_waitcnt lgkmcnt(0)
	v_add_f32_e32 v37, v120, v121
	v_mov_b32_e32 v120, v37
	v_mov_b32_e32 v121, v37
	s_nop 1
	v_permlane16_swap_b32_e32 v120, v121
	s_waitcnt lgkmcnt(0)
	v_add_f32_e32 v37, v120, v121
	s_nop 1
	s_waitcnt lgkmcnt(0)
	v_add_f32_dpp v37, v37, v37 row_ror:8 row_mask:0xf bank_mask:0xf
	s_nop 1
	v_mov_b32_dpp v120, v37 row_ror:4 row_mask:0xf bank_mask:0xa
	v_mov_b32_dpp v120, v37 row_ror:12 row_mask:0xf bank_mask:0x5
	s_waitcnt lgkmcnt(0)
	v_add_f32_e32 v37, v37, v120
	s_nop 1
	s_waitcnt lgkmcnt(0)
	v_add_f32_dpp v37, v37, v37 quad_perm:[2,3,0,1] row_mask:0xf bank_mask:0xf
	s_nop 1
	s_waitcnt lgkmcnt(0)
	v_add_f32_dpp v37, v37, v37 quad_perm:[1,0,3,2] row_mask:0xf bank_mask:0xf
	v_fmamk_f32 v37, v37, 0x3a000000, v245
	v_cmp_gt_f32_e32 vcc, s84, v37
	v_mul_f32_e32 v43, 0x4b800000, v37
	s_nop 0
	v_cndmask_b32_e32 v37, v37, v43, vcc
	v_rsq_f32_e32 v37, v37
	s_nop 0
	v_mul_f32_e32 v43, 0x45800000, v37
	v_cndmask_b32_e32 v94, v37, v43, vcc
	v_pk_mul_f32 v[70:71], v[70:71], v[94:95] op_sel_hi:[1,0]
	v_pk_mul_f32 v[72:73], v[72:73], v[94:95] op_sel_hi:[1,0]
	v_pk_fma_f32 v[30:31], v[102:103], v[70:71], v[30:31]
	v_pk_fma_f32 v[32:33], v[104:105], v[72:73], v[32:33]
	ds_read_b128 v[70:73], v95 offset:1024
	v_pk_mul_f32 v[74:75], v[74:75], v[94:95] op_sel_hi:[1,0]
	v_pk_mul_f32 v[76:77], v[76:77], v[94:95] op_sel_hi:[1,0]
	v_mul_f32_e32 v37, v31, v31
	v_fmac_f32_e32 v37, v30, v30
	s_waitcnt lgkmcnt(0)
	v_pk_fma_f32 v[28:29], v[72:73], v[76:77], v[28:29]
	v_pk_fma_f32 v[26:27], v[70:71], v[74:75], v[26:27]
	ds_read_b128 v[70:73], v95 offset:2048
	v_pk_mul_f32 v[74:75], v[78:79], v[94:95] op_sel_hi:[1,0]
	v_pk_mul_f32 v[76:77], v[80:81], v[94:95] op_sel_hi:[1,0]
	v_mul_f32_e32 v43, v27, v27
	v_fmac_f32_e32 v43, v26, v26
	s_waitcnt lgkmcnt(0)
	v_pk_fma_f32 v[24:25], v[72:73], v[76:77], v[24:25]
	v_pk_fma_f32 v[22:23], v[70:71], v[74:75], v[22:23]
	ds_read_b128 v[70:73], v95 offset:3072
	v_pk_mul_f32 v[74:75], v[82:83], v[94:95] op_sel_hi:[1,0]
	v_pk_mul_f32 v[76:77], v[84:85], v[94:95] op_sel_hi:[1,0]
	v_fmac_f32_e32 v37, v32, v32
	v_fmac_f32_e32 v43, v28, v28
	s_waitcnt lgkmcnt(0)
	v_pk_fma_f32 v[20:21], v[72:73], v[76:77], v[20:21]
	v_pk_fma_f32 v[18:19], v[70:71], v[74:75], v[18:19]
	ds_read_b128 v[70:73], v95 offset:4096
	v_mov_b32_e32 v74, v64
	v_mov_b32_e32 v75, v62
	v_mov_b32_e32 v76, v68
	v_mov_b32_e32 v77, v66
	v_pk_mul_f32 v[74:75], v[74:75], v[94:95] op_sel_hi:[1,0]
	v_pk_mul_f32 v[76:77], v[76:77], v[94:95] op_sel_hi:[1,0]
	s_waitcnt lgkmcnt(0)
	v_pk_fma_f32 v[14:15], v[70:71], v[74:75], v[14:15]
	v_pk_fma_f32 v[16:17], v[72:73], v[76:77], v[16:17]
	ds_read_b128 v[70:73], v95 offset:5120
	v_mov_b32_e32 v62, v65
	v_mov_b32_e32 v66, v69
	v_pk_mul_f32 v[62:63], v[62:63], v[94:95] op_sel_hi:[1,0]
	v_pk_mul_f32 v[64:65], v[66:67], v[94:95] op_sel_hi:[1,0]
	s_waitcnt lgkmcnt(0)
	v_pk_fma_f32 v[10:11], v[70:71], v[62:63], v[10:11]
	v_pk_fma_f32 v[12:13], v[72:73], v[64:65], v[12:13]
	ds_read_b128 v[62:65], v95 offset:6144
	v_mov_b32_e32 v66, v86
	v_mov_b32_e32 v67, v88
	v_mov_b32_e32 v68, v90
	v_mov_b32_e32 v69, v92
	v_pk_mul_f32 v[66:67], v[66:67], v[94:95] op_sel_hi:[1,0]
	v_pk_mul_f32 v[68:69], v[68:69], v[94:95] op_sel_hi:[1,0]
	s_waitcnt lgkmcnt(0)
; DI unsigned pack2(float lo, float hi) { f32x2 v = {lo, hi}; bf2_t b = __builtin_convertvector(v, bf2_t); return __builtin_bit_cast(unsigned, b); }
; DI float wave_sum(float v) { v += __shfl_xor(v, 32); v += __shfl_xor(v, 16); v += __shfl_xor(v, 8); v += __shfl_xor(v, 4); v += __shfl_xor(v, 2); v += __shfl_xor(v, 1); return v; }
; DI void rownorm_phase(const Params& P, const float* xin, const bf16_t* yin, float* xout, bf16_t* hout, int lg, int gate_idx, const float* w_post,
;                       int lh, int scale_idx, int shift_idx, const float* w_pre, char* smem) {
;     ...
;       for (int j = 0; j < 8; ++j) { const f32x4 a = *(const f32x4*)(A1 + (j * 64 + lane) * 4); xv[j] += a * (yv[j] * r); }
;     }
;     if (yin || xout != xin) {
; #pragma unroll
;       for (int j = 0; j < 8; ++j) __builtin_nontemporal_store(xv[j], (f32x4*)(xout + (size_t)row * 2048 + (j * 64 + lane) * 4));
;     }
;     if (hout) {
;       float ss = 0.f;
; #pragma unroll
;       for (int j = 0; j < 8; ++j) ss += xv[j].x * xv[j].x + xv[j].y * xv[j].y + xv[j].z * xv[j].z + xv[j].w * xv[j].w;
;       ss = wave_sum(ss); const float r = rsqrtf(ss * (1.f / 2048.f) + EPS);
; #pragma unroll
;       for (int j = 0; j < 8; ++j) { const f32x4 a = *(const f32x4*)(A2 + (j * 64 + lane) * 4), b = *(const f32x4*)(B2 + (j * 64 + lane) * 4);
;         const f32x4 hv = xv[j] * r * a + b; u32x2 pk = {pack2(hv.x, hv.y), pack2(hv.z, hv.w)};
;         *(u32x2*)(hout + (size_t)row * 2048 + (j * 64 + lane) * 4) = pk; }
	v_pk_fma_f32 v[6:7], v[62:63], v[66:67], v[6:7]
	v_pk_fma_f32 v[8:9], v[64:65], v[68:69], v[8:9]
	ds_read_b128 v[62:65], v95 offset:7168
	v_fmac_f32_e32 v37, v33, v33
	v_fmac_f32_e32 v43, v29, v29
	v_add_f32_e32 v37, v37, v43
	v_mul_f32_e32 v43, v23, v23
	v_fmac_f32_e32 v43, v22, v22
	v_mov_b32_e32 v88, v87
	v_mov_b32_e32 v92, v91
	v_fmac_f32_e32 v43, v24, v24
	v_pk_mul_f32 v[66:67], v[88:89], v[94:95] op_sel_hi:[1,0]
	v_pk_mul_f32 v[68:69], v[92:93], v[94:95] op_sel_hi:[1,0]
	v_fmac_f32_e32 v43, v25, v25
	s_waitcnt lgkmcnt(0)
	v_pk_fma_f32 v[4:5], v[64:65], v[68:69], v[4:5]
	v_pk_fma_f32 v[2:3], v[62:63], v[66:67], v[2:3]
	global_store_dwordx4 v[52:53], v[30:33], off nt
	global_store_dwordx4 v[52:53], v[26:29], off offset:1024 nt
	global_store_dwordx4 v[52:53], v[22:25], off offset:2048 nt
	global_store_dwordx4 v[52:53], v[18:21], off offset:3072 nt
	global_store_dwordx4 v[54:55], v[14:17], off nt
	global_store_dwordx4 v[56:57], v[10:13], off nt
	global_store_dwordx4 v[58:59], v[6:9], off nt
	global_store_dwordx4 v[60:61], v[2:5], off nt
	v_add_f32_e32 v37, v43, v37
	v_mul_f32_e32 v43, v19, v19
	v_mov_b32_e32 v54, v11
	v_mov_b32_e32 v55, v15
	v_fmac_f32_e32 v43, v18, v18
	v_mov_b32_e32 v52, v10
	v_mov_b32_e32 v53, v14
	v_pk_mul_f32 v[54:55], v[54:55], v[54:55]
	v_fmac_f32_e32 v43, v20, v20
	v_pk_fma_f32 v[52:53], v[52:53], v[52:53], v[54:55]
	v_mov_b32_e32 v54, v12
	v_mov_b32_e32 v55, v16
	v_fmac_f32_e32 v43, v21, v21
	v_pk_fma_f32 v[52:53], v[54:55], v[54:55], v[52:53]
	v_mov_b32_e32 v54, v13
	v_mov_b32_e32 v55, v17
	v_add_f32_e32 v37, v43, v37
	v_pk_fma_f32 v[52:53], v[54:55], v[54:55], v[52:53]
	v_mov_b32_e32 v54, v3
	v_add_f32_e32 v37, v53, v37
	v_mov_b32_e32 v55, v7
	v_add_f32_e32 v37, v52, v37
	v_mov_b32_e32 v52, v2
	v_mov_b32_e32 v53, v6
	v_pk_mul_f32 v[54:55], v[54:55], v[54:55]
	s_nop 0
	v_pk_fma_f32 v[52:53], v[52:53], v[52:53], v[54:55]
	v_mov_b32_e32 v54, v4
	v_mov_b32_e32 v55, v8
	v_pk_fma_f32 v[52:53], v[54:55], v[54:55], v[52:53]
	v_mov_b32_e32 v54, v5
	v_mov_b32_e32 v55, v9
	v_pk_fma_f32 v[52:53], v[54:55], v[54:55], v[52:53]
	ds_read_b128 v[54:57], v95 offset:8192
	ds_read_b128 v[58:61], v95 offset:16384
	v_add_f32_e32 v37, v53, v37
	v_add_f32_e32 v37, v52, v37
	v_mov_b32_e32 v120, v37
	v_mov_b32_e32 v121, v37
	s_nop 1
	v_permlane32_swap_b32_e32 v120, v121
	s_waitcnt lgkmcnt(0)
	v_add_f32_e32 v37, v120, v121
	v_mov_b32_e32 v120, v37
	v_mov_b32_e32 v121, v37
	s_nop 1
	v_permlane16_swap_b32_e32 v120, v121
	s_waitcnt lgkmcnt(0)
	v_add_f32_e32 v37, v120, v121
	s_nop 1
	s_waitcnt lgkmcnt(0)
	v_add_f32_dpp v37, v37, v37 row_ror:8 row_mask:0xf bank_mask:0xf
	s_nop 1
	v_mov_b32_dpp v120, v37 row_ror:4 row_mask:0xf bank_mask:0xa
	v_mov_b32_dpp v120, v37 row_ror:12 row_mask:0xf bank_mask:0x5
	s_waitcnt lgkmcnt(0)
	v_add_f32_e32 v37, v37, v120
	s_nop 1
	s_waitcnt lgkmcnt(0)
	v_add_f32_dpp v37, v37, v37 quad_perm:[2,3,0,1] row_mask:0xf bank_mask:0xf
	s_nop 1
	s_waitcnt lgkmcnt(0)
	v_add_f32_dpp v37, v37, v37 quad_perm:[1,0,3,2] row_mask:0xf bank_mask:0xf
	v_fmamk_f32 v37, v37, 0x3a000000, v245
	v_cmp_gt_f32_e32 vcc, s84, v37
	v_mul_f32_e32 v43, 0x4b800000, v37
	s_nop 0
	v_cndmask_b32_e32 v37, v37, v43, vcc
	v_rsq_f32_e32 v37, v37
	s_nop 0
	v_mul_f32_e32 v43, 0x45800000, v37
	v_cndmask_b32_e32 v52, v37, v43, vcc
	v_pk_mul_f32 v[30:31], v[30:31], v[52:53] op_sel_hi:[1,0]
	v_pk_mul_f32 v[32:33], v[32:33], v[52:53] op_sel_hi:[1,0]
	v_pk_fma_f32 v[30:31], v[54:55], v[30:31], v[58:59]
	v_pk_fma_f32 v[32:33], v[56:57], v[32:33], v[60:61]
	v_cvt_pk_bf16_f32 v54, v30, v31
	v_cvt_pk_bf16_f32 v55, v32, v33
	v_lshl_add_u64 v[30:31], v[40:41], 0, v[50:51]
	global_store_dwordx2 v[30:31], v[54:55], off
	ds_read_b128 v[54:57], v95 offset:9216
	ds_read_b128 v[58:61], v95 offset:17408
	v_pk_mul_f32 v[26:27], v[26:27], v[52:53] op_sel_hi:[1,0]
	v_pk_mul_f32 v[28:29], v[28:29], v[52:53] op_sel_hi:[1,0]
	v_pk_mul_f32 v[22:23], v[22:23], v[52:53] op_sel_hi:[1,0]
	v_pk_mul_f32 v[24:25], v[24:25], v[52:53] op_sel_hi:[1,0]
	s_waitcnt lgkmcnt(0)
	v_pk_fma_f32 v[28:29], v[56:57], v[28:29], v[60:61]
	v_pk_fma_f32 v[26:27], v[54:55], v[26:27], v[58:59]
	v_pk_mul_f32 v[18:19], v[18:19], v[52:53] op_sel_hi:[1,0]
	v_cvt_pk_bf16_f32 v26, v26, v27
	v_cvt_pk_bf16_f32 v27, v28, v29
	global_store_dwordx2 v[30:31], v[26:27], off offset:512
	ds_read_b128 v[26:29], v95 offset:10240
	ds_read_b128 v[54:57], v95 offset:18432
	v_pk_mul_f32 v[20:21], v[20:21], v[52:53] op_sel_hi:[1,0]
	v_pk_mul_f32 v[14:15], v[14:15], v[52:53] op_sel_hi:[1,0]
	v_pk_mul_f32 v[16:17], v[16:17], v[52:53] op_sel_hi:[1,0]
	v_pk_mul_f32 v[10:11], v[10:11], v[52:53] op_sel_hi:[1,0]
	s_waitcnt lgkmcnt(0)
	v_pk_fma_f32 v[24:25], v[28:29], v[24:25], v[56:57]
	v_pk_fma_f32 v[22:23], v[26:27], v[22:23], v[54:55]
	v_pk_mul_f32 v[12:13], v[12:13], v[52:53] op_sel_hi:[1,0]
	v_cvt_pk_bf16_f32 v22, v22, v23
	v_cvt_pk_bf16_f32 v23, v24, v25
	global_store_dwordx2 v[30:31], v[22:23], off offset:1024
	ds_read_b128 v[22:25], v95 offset:11264
	ds_read_b128 v[26:29], v95 offset:19456
	v_pk_mul_f32 v[6:7], v[6:7], v[52:53] op_sel_hi:[1,0]
	v_pk_mul_f32 v[8:9], v[8:9], v[52:53] op_sel_hi:[1,0]
	v_pk_mul_f32 v[2:3], v[2:3], v[52:53] op_sel_hi:[1,0]
	v_pk_mul_f32 v[4:5], v[4:5], v[52:53] op_sel_hi:[1,0]
	s_waitcnt lgkmcnt(0)
	v_pk_fma_f32 v[20:21], v[24:25], v[20:21], v[28:29]
	v_pk_fma_f32 v[18:19], v[22:23], v[18:19], v[26:27]
	v_cmp_lt_i32_e32 vcc, s4, v36
	v_cvt_pk_bf16_f32 v18, v18, v19
	v_cvt_pk_bf16_f32 v19, v20, v21
	global_store_dwordx2 v[30:31], v[18:19], off offset:1536
	ds_read_b128 v[18:21], v95 offset:12288
	ds_read_b128 v[22:25], v95 offset:20480
	s_or_b64 s[2:3], vcc, s[2:3]
	s_waitcnt lgkmcnt(0)
	v_pk_fma_f32 v[16:17], v[20:21], v[16:17], v[24:25]
	v_pk_fma_f32 v[14:15], v[18:19], v[14:15], v[22:23]
	s_nop 0
	v_cvt_pk_bf16_f32 v14, v14, v15
	v_cvt_pk_bf16_f32 v15, v16, v17
	global_store_dwordx2 v[30:31], v[14:15], off offset:2048
	ds_read_b128 v[14:17], v95 offset:13312
	ds_read_b128 v[18:21], v95 offset:21504
	s_waitcnt lgkmcnt(0)
	v_pk_fma_f32 v[12:13], v[16:17], v[12:13], v[20:21]
	v_pk_fma_f32 v[10:11], v[14:15], v[10:11], v[18:19]
	s_nop 0
	v_cvt_pk_bf16_f32 v10, v10, v11
	v_cvt_pk_bf16_f32 v11, v12, v13
	global_store_dwordx2 v[30:31], v[10:11], off offset:2560
	ds_read_b128 v[10:13], v95 offset:14336
	ds_read_b128 v[14:17], v95 offset:22528
	s_waitcnt lgkmcnt(0)
	v_pk_fma_f32 v[8:9], v[12:13], v[8:9], v[16:17]
	v_pk_fma_f32 v[6:7], v[10:11], v[6:7], v[14:15]
	s_nop 0
	v_cvt_pk_bf16_f32 v6, v6, v7
	v_cvt_pk_bf16_f32 v7, v8, v9
	global_store_dwordx2 v[30:31], v[6:7], off offset:3072
	ds_read_b128 v[6:9], v95 offset:15360
	ds_read_b128 v[10:13], v95 offset:23552
	s_waitcnt lgkmcnt(0)
	v_pk_fma_f32 v[4:5], v[8:9], v[4:5], v[12:13]
	v_pk_fma_f32 v[2:3], v[6:7], v[2:3], v[10:11]
	s_nop 0
	v_cvt_pk_bf16_f32 v2, v2, v3
	v_cvt_pk_bf16_f32 v3, v4, v5
	global_store_dwordx2 v[30:31], v[2:3], off offset:3584
	s_andn2_b64 exec, exec, s[2:3]
	s_cbranch_execnz .LBB0_1236
